# GEMM tile loop header: next tile coordinates computed directly on the 256-workgroup grid (generic swizzle/division chain kept as fallback)
# speedup vs baseline: 1.0160x; 1.0044x over previous
;     __host__ __device__ bool next(int i, Unit& u) const {
;         const long L = (long)i * G + c; if (L >= nwg) return false;
;         int wgid = (int)L; { const int q = nwg / NXCD, r = nwg % NXCD, xcd = wgid % NXCD, off = wgid / NXCD; wgid = (xcd < r ? xcd * (q + 1) : r * (q + 1) + (xcd - r) * q) + off; }
;         const int nig = WGM * nN, gid = wgid / nig, fm = gid * WGM, gsz = (nM - fm) < WGM ? (nM - fm) : WGM;
;         u.pm = fm + ((wgid % nig) % gsz); u.pn = (wgid % nig) / gsz; return true;
;     }
.LBB0_52:
	s_add_i32 s72, s72, 1
	v_readlane_b32 s4, v238, 15
	v_readlane_b32 s26, v238, 6
	s_mul_i32 s4, s72, s4
	s_mul_hi_u32 s5, s72, s26
	s_add_i32 s5, s5, s4
	s_mul_i32 s4, s72, s26
	v_readlane_b32 s27, v238, 7
	s_add_u32 s26, s4, s92
	v_readlane_b32 s4, v238, 14
	s_addc_u32 s27, s5, s4
	v_mov_b64_e32 v[2:3], s[14:15]
	v_cmp_ge_i64_e32 vcc, s[26:27], v[2:3]
	v_cmp_lt_i64_e64 s[4:5], s[26:27], v[2:3]
	s_cbranch_vccnz .LBB0_54
	v_readlane_b32 s17, v238, 6
	s_and_b32 s20, s92, 7
	s_lshl_b32 s20, s20, 3
	s_bfe_u32 s74, s92, 0x30003
	s_cmpk_lg_i32 s17, 0x100
	s_cbranch_scc1 .Lmy_hdr_slow
	s_add_i32 s74, s74, s20
	s_lshr_b32 s17, s92, 6
	s_lshl_b32 s20, s72, 2
	s_add_i32 s17, s17, s20
	s_branch .LBB0_54
.Lmy_hdr_slow:
	s_ashr_i32 s17, s26, 31
	s_lshr_b32 s17, s17, 29
	s_add_i32 s17, s26, s17
	s_ashr_i32 s20, s17, 3
	s_and_b32 s17, s17, -8
	s_sub_i32 s17, s26, s17
	s_lshr_b32 s26, s17, 31
	s_or_b32 s26, s71, s26
	s_mul_i32 s17, s26, s17
	s_add_i32 s17, s17, s20
	s_abs_i32 s26, s17
	s_mul_hi_u32 s27, s26, s73
	s_mul_i32 s28, s27, s71
	s_sub_i32 s26, s26, s28
	s_ashr_i32 s20, s17, 31
	s_add_i32 s28, s27, 1
	s_sub_i32 s29, s26, s71
	s_cmp_ge_u32 s26, s71
	s_cselect_b32 s27, s28, s27
	s_cselect_b32 s26, s29, s26
	s_add_i32 s28, s27, 1
	s_cmp_ge_u32 s26, s71
	s_cselect_b32 s26, s28, s27
	s_xor_b32 s26, s26, s20
	s_sub_i32 s20, s26, s20
	s_lshl_b32 s26, s20, 3
	s_sub_i32 s27, 64, s26
	s_min_i32 s27, s27, 8
	s_abs_i32 s28, s27
	v_cvt_f32_u32_e32 v2, s28
	s_sub_i32 s44, 0, s28
	s_mul_i32 s20, s20, s71
	s_sub_i32 s20, s17, s20
	v_rcp_iflag_f32_e32 v2, v2
	s_abs_i32 s29, s20
	s_xor_b32 s17, s20, s27
	s_ashr_i32 s17, s17, 31
	v_mul_f32_e32 v2, 0x4f7ffffe, v2
	v_cvt_u32_f32_e32 v2, v2
	s_nop 0
	v_readfirstlane_b32 s45, v2
	s_mul_i32 s44, s44, s45
	s_mul_hi_u32 s44, s45, s44
	s_add_i32 s45, s45, s44
	s_mul_hi_u32 s44, s29, s45
	s_mul_i32 s45, s44, s28
	s_sub_i32 s29, s29, s45
	s_add_i32 s45, s44, 1
	s_sub_i32 s46, s29, s28
	s_cmp_ge_u32 s29, s28
	s_cselect_b32 s44, s45, s44
	s_cselect_b32 s29, s46, s29
	s_add_i32 s45, s44, 1
	s_cmp_ge_u32 s29, s28
	s_cselect_b32 s28, s45, s44
	s_xor_b32 s28, s28, s17
	s_sub_i32 s17, s28, s17
	s_mul_i32 s27, s17, s27
	s_sub_i32 s20, s20, s27
	s_add_i32 s74, s20, s26
